# cached-row up-projection unit (XCDs 4-7) moved from the k_a-tile workgroups to the krope-tile workgroups, whose bf16 unit is now mostly skipped
# speedup vs baseline: 1.0064x; 1.0012x over previous
.LBB0_895:
	s_ashr_i32 s84, s90, 31
	s_lshr_b32 s2, s84, 29
	s_add_i32 s2, s90, s2
	s_and_b32 s3, s2, -8
	s_sub_i32 s8, s90, s3
	s_and_b32 s3, s90, 7
	s_ashr_i32 s18, s90, 3
	s_lshl_b32 s4, s3, 3
	s_add_i32 s9, s18, s4
	s_and_b32 s10, s18, 7
	s_sub_i32 s12, s9, 24
	s_or_b32 s20, s10, s4
	s_and_b32 s4, s90, 0xffffffc0
	s_cmp_eq_u32 s4, 64
	s_cselect_b32 s6, 12, 13
	s_cmp_gt_u32 s18, 7
	s_cselect_b64 s[4:5], -1, 0
	v_writelane_b32 v253, s4, 6
	s_movk_i32 s7, 0x71
	s_mov_b32 s85, 0x3fc00000
	v_writelane_b32 v253, s5, 7
	s_and_b64 s[4:5], s[4:5], exec
	s_cselect_b32 s11, s6, 4
	s_lshl_b32 s6, s8, 6
	s_cmp_lt_i32 s18, 24
	s_cselect_b64 s[4:5], -1, 0
	s_and_b64 s[4:5], s[4:5], exec
	s_cselect_b32 s4, s20, s12
	s_cmp_lt_i32 s8, 0
	s_mul_i32 s5, s8, 0x41
	s_cselect_b32 s13, s7, 0x70
	s_movk_i32 s7, 0x45
	s_cselect_b32 s15, s5, s6
	s_movk_i32 s5, 0x161
	s_cselect_b32 s14, s7, 0x44
	s_cselect_b32 s16, s5, 0x160
	s_cmp_lt_i32 s18, 24
	s_cselect_b64 s[6:7], -1, 0
	v_writelane_b32 v253, s6, 8
	s_mul_i32 s13, s8, s13
	s_mov_b32 s36, 0
	v_writelane_b32 v253, s7, 9
	s_and_b64 s[6:7], s[6:7], exec
	s_cselect_b32 s5, 0, 48
	s_cselect_b32 s19, s11, 11
	s_cmpk_lg_i32 s88, 0x100
	s_cselect_b64 s[6:7], -1, 0
	v_writelane_b32 v253, s6, 10
	s_cmpk_eq_i32 s88, 0x100
	v_mov_b32_e32 v242, 0x260
	v_writelane_b32 v253, s7, 11
	s_cselect_b64 s[6:7], -1, 0
	v_writelane_b32 v253, s6, 12
	s_cmpk_lt_i32 s90, 0x380
	v_writelane_b32 v255, s90, 0
	v_writelane_b32 v253, s7, 13
	s_cselect_b64 s[6:7], -1, 0
	s_ashr_i32 s17, s2, 3
	v_writelane_b32 v253, s6, 14
	s_cmp_gt_i32 s18, 23
	v_writelane_b32 v255, s91, 1
	v_writelane_b32 v253, s7, 15
	s_cselect_b64 s[6:7], -1, 0
	s_sub_i32 s2, s9, 56
	s_lshr_b32 s2, s2, 3
	s_mul_i32 s2, s2, 9
	s_add_i32 s2, s10, s2
	s_add_i32 s5, s5, s18
	s_add_i32 s9, s2, 33
	s_ashr_i32 s2, s5, 3
	v_writelane_b32 v253, s6, 16
	s_cmp_gt_i32 s2, 3
	v_mov_b32_e32 v243, 0x3000
	v_writelane_b32 v253, s7, 17
	s_cselect_b64 s[6:7], -1, 0
	s_cmp_lg_u64 s[6:7], 0
	s_addc_u32 s10, s2, 0
	s_lshl_b32 s2, s20, 19
	v_writelane_b32 v253, s2, 18
	s_mov_b32 s6, s10
	s_ashr_i32 s11, s10, 31
	v_writelane_b32 v253, s6, 19
	s_mul_i32 s2, s3, 9
	v_mov_b32_e32 v251, 1
	v_writelane_b32 v253, s7, 20
	s_lshl_b64 s[6:7], s[10:11], 19
	v_writelane_b32 v253, s6, 21
	s_cmp_gt_u32 s3, 3
	v_mov_b32_e32 v252, 0x5000
	v_writelane_b32 v253, s7, 22
	s_cselect_b64 s[6:7], -1, 0
	s_sub_i32 s100, s18, 16
	s_cmp_lt_u32 s100, 8
	s_cselect_b64 s[10:11], -1, 0
	s_and_b64 s[6:7], s[6:7], s[10:11]
	v_writelane_b32 v253, s6, 23
	s_add_i32 s2, s2, -4
	s_ashr_i32 s5, s2, 31
	v_writelane_b32 v253, s7, 24
	v_writelane_b32 v253, s5, 25
	s_ashr_i32 s5, s18, 31
	v_writelane_b32 v253, s5, 26
	v_writelane_b32 v253, s2, 27
	s_lshl_b32 s2, s2, 8
	v_writelane_b32 v253, s2, 28
	s_lshl_b32 s2, s18, 8
	s_and_b32 s2, s2, 0x300
	v_writelane_b32 v253, s2, 29
	s_cmp_lt_i32 s18, 4
	v_writelane_b32 v253, s18, 30
	s_cselect_b32 s2, s85, 0x41e00000
	s_cmpk_lt_i32 s90, 0x220
	v_writelane_b32 v253, s2, 31
	s_cselect_b64 s[6:7], -1, 0
	v_writelane_b32 v253, s6, 32
	s_cmpk_lt_i32 s90, 0x200
	v_mov_b32_e32 v246, 0x6000
	v_writelane_b32 v253, s7, 33
	s_cselect_b64 s[6:7], -1, 0
	s_lshl_b32 s2, s90, 2
	v_writelane_b32 v253, s6, 34
	s_and_b32 s5, s2, 28
	s_bfe_u32 s18, s90, 0x20003
	v_writelane_b32 v253, s7, 35
	s_or_b32 s7, s5, s18
	s_or_b32 s5, s7, 32
	s_ashr_i32 s10, s90, 5
	s_lshl_b32 s6, s5, 19
	v_writelane_b32 v253, s6, 36
	s_bfe_u32 s6, s2, 0x20003
	s_lshl_b32 s2, s10, 8
	v_writelane_b32 v253, s2, 37
	s_lshl_b32 s2, s5, 8
	s_ashr_i32 s11, s10, 31
	v_writelane_b32 v253, s2, 38
	s_lshl_b32 s2, s7, 20
	s_lshl_b64 s[22:23], s[10:11], 19
	v_writelane_b32 v253, s2, 39
	s_lshl_b64 s[24:25], s[10:11], 20
	s_lshl_b32 s2, s7, 8
	s_cmpk_lt_i32 s90, 0xb00
	s_cselect_b64 s[10:11], -1, 0
	s_add_i32 s13, s13, s17
	v_writelane_b32 v253, s2, 40
	s_mul_hi_i32 s2, s13, 0x92492493
	s_add_i32 s2, s2, s13
	s_lshr_b32 s5, s2, 31
	s_ashr_i32 s2, s2, 6
	s_add_i32 s2, s2, s5
	s_mul_i32 s5, s2, 0x70
	v_writelane_b32 v253, s10, 41
	s_sub_i32 s5, s13, s5
	s_lshl_b32 s21, s19, 20
	v_writelane_b32 v253, s11, 42
	s_lshl_b32 s10, s2, 3
	s_bfe_i32 s2, s5, 0x80000
	s_bfe_u32 s2, s2, 0x3000c
	s_add_i32 s11, s5, s2
	s_bfe_i32 s2, s11, 0x80000
	s_and_b32 s11, s11, 0xf8
	s_sub_i32 s5, s5, s11
	s_sext_i32_i16 s13, s2
	s_sext_i32_i8 s11, s5
	s_mov_b32 s5, s36
	s_lshr_b32 s2, s13, 3
	s_add_i32 s26, s10, s11
	s_ashr_i32 s10, s13, 3
	s_lshl_b64 s[28:29], s[4:5], 20
	s_cmp_lt_u32 s4, 32
	v_writelane_b32 v253, s10, 43
	s_cselect_b64 s[10:11], -1, 0
	v_writelane_b32 v253, s10, 44
	s_lshl_b32 s5, s4, 5
	s_and_b32 s5, s5, 0xffffff00
	v_writelane_b32 v253, s11, 45
	s_lshl_b32 s10, s4, 8
	s_addk_i32 s5, 0xfd00
	s_and_b32 s13, s10, 0x700
	s_cmp_gt_u32 s4, 31
	v_writelane_b32 v253, s10, 46
	s_cselect_b64 s[10:11], -1, 0
	v_writelane_b32 v253, s10, 47
	v_bfrev_b32_e32 v247, 0.5
	v_mov_b32_e32 v248, 0xf149f2ca
	v_writelane_b32 v253, s11, 48
	s_and_b64 s[10:11], s[10:11], exec
	s_cselect_b32 s5, s5, 0
	s_cselect_b32 s10, s13, 0
	s_cmp_eq_u32 s19, 13
	v_writelane_b32 v253, s10, 49
	s_cselect_b64 s[10:11], -1, 0
	v_writelane_b32 v253, s10, 50
	s_cmp_lg_u32 s19, 13
	s_movk_i32 s87, 0x70
	v_writelane_b32 v253, s11, 51
	s_cselect_b64 s[10:11], -1, 0
	v_writelane_b32 v253, s10, 52
	s_lshl_b32 s4, s4, 10
	s_movk_i32 s33, 0x1000
	v_writelane_b32 v253, s11, 53
	s_or_b32 s10, s4, 16
	v_writelane_b32 v253, s10, 54
	s_or_b32 s10, s4, 32
	v_writelane_b32 v253, s10, 55
	v_writelane_b32 v253, s4, 56
	s_or_b32 s4, s4, 48
	v_writelane_b32 v253, s4, 57
	s_or_b32 s4, s5, 0x80
	v_writelane_b32 v253, s4, 58
	s_or_b32 s4, s5, 0x90
	v_writelane_b32 v253, s4, 59
	s_or_b32 s4, s5, 0xa0
	v_writelane_b32 v253, s4, 60
	s_or_b32 s4, s5, 0xb0
	v_writelane_b32 v253, s4, 61
	s_mov_b32 s4, s20
	v_writelane_b32 v253, s4, 62
	s_movk_i32 s31, 0xffe0
	s_mov_b32 s80, 0x428a9067
	v_writelane_b32 v253, s5, 63
	s_lshl_b32 s4, s20, 10
	v_writelane_b32 v254, s4, 0
	s_or_b32 s4, s5, 16
	v_writelane_b32 v254, s4, 1
	s_or_b32 s4, s5, 32
	v_writelane_b32 v254, s4, 2
	v_writelane_b32 v254, s5, 3
	s_or_b32 s4, s5, 48
	s_lshl_b32 s20, s19, 8
	v_writelane_b32 v254, s4, 4
	s_cmp_lt_i32 s12, 32
	s_mul_i32 s4, s8, s14
	s_cselect_b32 s30, s12, s9
	s_add_i32 s4, s4, s17
	s_ashr_i32 s5, s4, 31
	s_lshr_b32 s5, s5, 26
	s_add_i32 s5, s4, s5
	s_and_b32 s9, s5, 0xffffffc0
	s_sub_i32 s9, s4, s9
	s_add_i32 s4, s15, s17
	s_ashr_i32 s10, s4, 31
	s_lshr_b32 s10, s10, 26
	s_add_i32 s10, s4, s10
	s_and_b32 s11, s10, 0xffc0
	s_sub_i32 s4, s4, s11
	s_bfe_i32 s11, s4, 0x80000
	s_bfe_u32 s11, s11, 0x3000c
	s_add_i32 s11, s4, s11
	s_mul_i32 s8, s8, s16
	s_and_b32 s12, s11, 0xf8
	s_add_i32 s8, s8, s17
	s_sub_i32 s4, s4, s12
	s_mul_hi_i32 s12, s8, 0x2e8ba2e9
	s_lshr_b32 s13, s12, 31
	s_ashr_i32 s12, s12, 6
	s_add_i32 s12, s12, s13
	s_mul_i32 s13, s12, 0x160
	s_sub_i32 s8, s8, s13
	s_bfe_u32 s13, s8, 0x3001c
	s_add_i32 s13, s8, s13
	s_and_b32 s14, s13, 0xfff8
	s_ashr_i32 s5, s5, 6
	s_sub_i32 s8, s8, s14
	s_lshl_b32 s14, s5, 3
	s_sub_i32 s5, 0x44, s14
	s_min_u32 s15, s5, 8
	s_ashr_i32 s5, s10, 6
	s_bfe_i32 s10, s11, 0x80000
	s_lshl_b32 s5, s5, 3
	s_sext_i32_i16 s10, s10
	s_sext_i32_i8 s4, s4
	s_add_i32 s16, s5, s4
	s_ashr_i32 s4, s10, 3
	v_writelane_b32 v254, s4, 5
	s_lshr_b32 s4, s10, 3
	s_bfe_i64 s[4:5], s[4:5], 0x100000
	s_lshl_b64 s[4:5], s[4:5], 20
	v_writelane_b32 v254, s4, 6
	s_sext_i32_i16 s8, s8
	s_ashr_i32 s17, s16, 31
	v_writelane_b32 v254, s5, 7
	s_lshl_b32 s4, s12, 3
	s_sext_i32_i16 s5, s13
	s_add_i32 s10, s4, s8
	s_ashr_i32 s4, s5, 3
	v_writelane_b32 v254, s4, 8
	s_lshr_b32 s4, s5, 3
	s_bfe_i64 s[4:5], s[4:5], 0x100000
	s_lshl_b64 s[4:5], s[4:5], 20
	v_writelane_b32 v254, s4, 9
	s_waitcnt vmcnt(1)
	v_cvt_f32_ubyte0_e32 v2, s15
	s_ashr_i32 s11, s10, 31
	v_writelane_b32 v254, s5, 10
	s_bfe_i64 s[4:5], s[2:3], 0x100000
	s_lshl_b64 s[4:5], s[4:5], 20
	v_writelane_b32 v254, s4, 11
	v_cvt_f32_i32_e32 v1, s9
	v_rcp_iflag_f32_e32 v3, v2
	v_writelane_b32 v254, s5, 12
	v_writelane_b32 v254, s30, 13
	s_ashr_i32 s4, s30, 31
	v_writelane_b32 v254, s4, 14
	s_mov_b32 s4, s16
	v_writelane_b32 v254, s4, 15
	s_ashr_i32 s27, s26, 31
	v_mul_f32_e32 v3, v1, v3
	v_writelane_b32 v254, s5, 16
	s_lshl_b64 s[4:5], s[16:17], 20
	v_writelane_b32 v254, s4, 17
	v_trunc_f32_e32 v3, v3
	v_fma_f32 v1, -v3, v2, v1
	v_writelane_b32 v254, s5, 18
	s_mov_b32 s4, s10
	v_writelane_b32 v254, s4, 19
	s_ashr_i32 s2, s9, 30
	s_or_b32 s2, s2, 1
	v_writelane_b32 v254, s5, 20
	s_lshl_b64 s[4:5], s[10:11], 20
	v_writelane_b32 v254, s4, 21
	s_mov_b32 s17, 0xf800000
	s_movk_i32 s30, 0x60
	v_writelane_b32 v254, s5, 22
	s_mov_b32 s4, s26
	v_writelane_b32 v254, s4, 23
	s_mov_b32 s81, 0x42624630
	s_mov_b64 s[54:55], 0x1000
	v_writelane_b32 v254, s5, 24
	s_lshl_b64 s[4:5], s[26:27], 20
	v_writelane_b32 v254, s4, 25
	s_mov_b64 s[62:63], 0x1800
	s_mov_b64 s[64:65], 0x80
	v_writelane_b32 v254, s5, 26
	v_cmp_ge_f32_e64 s[4:5], |v1|, v2
	v_cvt_i32_f32_e32 v1, v3
	s_and_b64 s[4:5], s[4:5], exec
	s_cselect_b32 s2, s2, 0
	v_mov_b32_e32 v3, 0
	v_readfirstlane_b32 s4, v1
	s_add_i32 s2, s4, s2
	s_mul_i32 s4, s2, s15
	s_sub_i32 s4, s9, s4
	s_sext_i32_i8 s4, s4
	s_add_i32 s4, s14, s4
	v_writelane_b32 v254, s4, 27
	s_ashr_i32 s4, s4, 31
	s_sext_i32_i8 s2, s2
	v_writelane_b32 v254, s4, 28
	v_writelane_b32 v254, s2, 29
	s_ashr_i32 s2, s2, 31
	v_writelane_b32 v254, s2, 30
	s_add_u32 s2, s28, 0x20480080
	v_writelane_b32 v254, s2, 31
	v_writelane_b32 v254, s28, 32
	s_addc_u32 s2, s29, 0
	s_or_b32 s4, s21, 0x2000100
	v_writelane_b32 v254, s29, 33
	v_writelane_b32 v254, s2, 34
	s_mul_i32 s2, s3, 0x1200
	s_add_u32 s2, s2, 0xfffff900
	v_writelane_b32 v254, s2, 35
	s_lshl_b32 s2, s7, 19
	v_writelane_b32 v254, s21, 36
	s_bitset1_b32 s2, 24
	v_writelane_b32 v254, s4, 37
	v_writelane_b32 v254, s2, 38
	s_add_u32 s2, s2, 0x45c40080
	v_writelane_b32 v254, s2, 39
	s_addc_u32 s2, 0, 0
	v_writelane_b32 v254, s2, 40
	s_add_u32 s2, s22, 0x47c00100
	v_writelane_b32 v254, s2, 41
	v_writelane_b32 v254, s22, 42
	s_addc_u32 s2, s23, 0
	s_mov_b32 s21, s36
	v_writelane_b32 v254, s23, 43
	v_writelane_b32 v254, s2, 44
	v_writelane_b32 v254, s18, 45
	s_lshl_b32 s2, s3, 22
	s_lshl_b32 s3, s18, 20
	v_writelane_b32 v254, s20, 46
	s_or_b32 s3, s2, s3
	s_mul_i32 s2, s6, 0x3000
	v_writelane_b32 v254, s21, 47
	v_writelane_b32 v254, s3, 48
	s_add_u32 s3, s3, 0x34480080
	v_writelane_b32 v254, s3, 49
	s_addc_u32 s3, 0, 0
	v_writelane_b32 v254, s3, 50
	s_add_u32 s3, s24, 0x5800100
	v_writelane_b32 v254, s3, 51
	v_writelane_b32 v254, s24, 52
	s_addc_u32 s3, s25, 0
	s_lshl_b32 s2, s2, 2
	v_writelane_b32 v254, s25, 53
	v_writelane_b32 v254, s3, 54
	v_writelane_b32 v254, s2, 55
	s_mov_b32 s2, s36
	v_writelane_b32 v254, s2, 56
	v_writelane_b32 v254, s19, 57
	s_add_i32 s2, s19, -9
	v_writelane_b32 v254, s2, 58
	s_mov_b64 s[2:3], 0x3cc00080
	v_writelane_b32 v254, s2, 59
	v_mov_b32_e32 v1, 0x358637bd
	s_mov_b64 s[28:29], 0x20000
	v_writelane_b32 v254, s3, 60
	s_mov_b64 s[2:3], 0
	v_writelane_b32 v254, s2, 61
	s_mov_b32 s86, 0x3dd53b94
	s_mov_b64 s[60:61], 0x8000
	v_writelane_b32 v254, s3, 62
	s_mov_b32 s72, 0x3e0293ee
	s_mov_b64 s[94:95], 0
	s_mov_b32 s66, 0
	v_writelane_b32 v254, s89, 63
	v_writelane_b32 v255, s84, 2
	s_branch .LBB0_899

.LBB0_2324:
	v_writelane_b32 v253, s58, 62
	s_waitcnt vmcnt(0)
	s_barrier
	s_load_dword s88, s[0:1], 0xd0
	s_load_dwordx4 s[68:71], s[0:1], 0xc0
	v_writelane_b32 v253, s59, 63
	v_readlane_b32 s66, v255, 6
	v_readlane_b32 s2, v253, 23
	v_readlane_b32 s3, v253, 24
	s_andn2_b64 vcc, exec, s[2:3]
	v_readlane_b32 s89, v254, 63
	v_readlane_b32 s90, v255, 0
	v_readlane_b32 s91, v255, 1
	v_readlane_b32 s58, v253, 5
	v_readlane_b32 s84, v255, 2
	s_mov_b32 s85, 0x3fc00000
	v_readlane_b32 s67, v255, 7
	v_readlane_b32 s48, v255, 3
	v_readlane_b32 s43, v255, 36
	s_cbranch_vccnz .LBB0_2333
	s_movk_i32 s8, 0x100
	v_mov_b32_e32 v138, v0
	v_mov_b32_e32 v2, 0x7f7f7f7f
	v_mov_b32_e32 v4, 0x7f7f7f7f
	v_readlane_b32 s2, v255, 8
	v_bfe_i32 v5, v138, 27, 1
	v_lshlrev_b32_e32 v4, 4, v138
	v_lshrrev_b32_e32 v5, 22, v5
	v_add_u32_e32 v5, v4, v5
	v_and_b32_e32 v5, 0xfffffc00, v5
	v_sub_u32_e32 v5, v4, v5
	v_ashrrev_i32_e32 v2, 31, v138
	v_lshrrev_b32_e32 v6, 4, v5
	v_lshrrev_b32_e32 v2, 26, v2
	v_bitop3_b32 v5, v6, v5, 32 bitop3:0x6c
	v_add_u32_e32 v2, v138, v2
	v_ashrrev_i32_e32 v7, 31, v5
	v_ashrrev_i32_e32 v2, 6, v2
	v_lshrrev_b32_e32 v7, 26, v7
	v_readlane_b32 s3, v255, 31
	v_lshlrev_b32_e32 v6, 3, v2
	v_add_u32_e32 v7, v5, v7
	s_add_u32 s6, s3, s2
	v_readlane_b32 s2, v255, 9
	v_readlane_b32 s3, v255, 32
	v_and_b32_e32 v6, -16, v6
	v_ashrrev_i32_e32 v8, 6, v7
	v_lshlrev_b32_e32 v2, 5, v2
	s_addc_u32 s7, s3, s2
	s_lshl_b64 s[2:3], s[66:67], 20
	v_add_u32_e32 v6, v8, v6
	v_and_b32_e32 v139, 32, v2
	v_and_b32_e32 v2, 0xc0, v7
	s_add_u32 s10, s38, s2
	v_sub_u32_e32 v2, v5, v2
	v_lshlrev_b32_e32 v5, 1, v6
	v_lshrrev_b32_e32 v7, 2, v6
	v_and_b32_e32 v8, 3, v8
	s_mov_b32 s2, 0x7fffffe0
	v_ashrrev_i16_sdwa v2, v251, sext(v2) dst_sel:DWORD dst_unused:UNUSED_PAD src0_sel:DWORD src1_sel:BYTE_0
	v_and_b32_e32 v5, 24, v5
	v_and_b32_e32 v7, 4, v7
	v_and_or_b32 v8, v6, s2, v8
	v_bfe_i32 v140, v2, 0, 16
	v_or3_b32 v5, v8, v7, v5
	v_add_u32_e32 v2, v139, v140
	v_mul_lo_u32 v141, v6, s8
	v_mul_lo_u32 v5, v5, s8
	v_add_u32_e32 v4, 0x2000, v4
	v_add_lshl_u32 v132, v2, v141, 1
	v_add_lshl_u32 v2, v5, v2, 1
	v_ashrrev_i32_e32 v5, 31, v4
	v_lshrrev_b32_e32 v5, 22, v5
	v_add_u32_e32 v5, v4, v5
	v_ashrrev_i32_e32 v5, 10, v5
	v_mul_i32_i24_e32 v6, 0x400, v5
	v_sub_u32_e32 v4, v4, v6
	s_addc_u32 s11, s39, s3
	v_lshrrev_b32_e32 v6, 4, v4
	s_lshl_b32 s15, s8, 9
	v_readlane_b32 s4, v253, 25
	v_readlane_b32 s18, v253, 27
	v_bitop3_b32 v4, v6, v4, 32 bitop3:0x6c
	s_ashr_i32 s9, s8, 31
	s_mul_i32 s4, s15, s4
	s_mul_hi_u32 s5, s15, s18
	v_ashrrev_i32_e32 v7, 31, v4
	s_add_i32 s16, s5, s4
	s_lshr_b64 s[4:5], s[8:9], 23
	v_lshrrev_b32_e32 v7, 26, v7
	s_mul_i32 s5, s4, s18
	v_lshlrev_b32_e32 v6, 3, v5
	v_add_u32_e32 v7, v4, v7
	s_add_i32 s16, s16, s5
	v_readlane_b32 s5, v253, 26
	v_readlane_b32 s19, v253, 30
	v_readfirstlane_b32 s14, v138
	s_sub_i32 s19, s19, 16
	v_and_b32_e32 v6, -16, v6
	v_ashrrev_i32_e32 v8, 6, v7
	s_mul_i32 s22, s15, s18
	s_mul_i32 s5, s15, s5
	s_mul_hi_u32 s18, s15, s19
	s_ashr_i32 s13, s14, 6
	v_add_u32_e32 v6, v8, v6
	v_and_b32_e32 v8, 3, v8
	s_add_i32 s5, s18, s5
	s_mul_i32 s4, s4, s19
	v_and_or_b32 v8, v6, s2, v8
	s_ashr_i32 s12, s14, 8
	s_lshl_b64 s[2:3], s[8:9], 8
	s_lshl_b32 s37, s13, 10
	s_add_i32 s5, s5, s4
	s_mul_i32 s15, s15, s19
	s_add_u32 s4, s10, s15
	s_addc_u32 s5, s11, s5
	v_lshlrev_b32_e32 v5, 5, v5
	s_add_u32 s4, s4, 0x18000000
	v_and_b32_e32 v143, 32, v5
	v_and_b32_e32 v5, 0xc0, v7
	s_addc_u32 s5, s5, 0
	s_add_i32 s18, s83, s37
	v_sub_u32_e32 v4, v4, v5
	v_lshlrev_b32_e32 v5, 1, v6
	v_lshrrev_b32_e32 v7, 2, v6
	s_add_i32 s19, s18, 0x2000
	v_ashrrev_i16_sdwa v4, v251, sext(v4) dst_sel:DWORD dst_unused:UNUSED_PAD src0_sel:DWORD src1_sel:BYTE_0
	v_and_b32_e32 v5, 24, v5
	v_and_b32_e32 v7, 4, v7
	s_add_u32 s10, s4, s2
	v_bfe_i32 v144, v4, 0, 16
	v_or3_b32 v5, v8, v7, v5
	s_addc_u32 s11, s5, s3
	s_add_i32 s20, s44, s37
	v_add_u32_e32 v4, v143, v144
	v_mul_lo_u32 v5, v5, s8
	s_mov_b32 m0, s18
	s_add_i32 s21, s20, 0x2000
	v_add_lshl_u32 v136, v5, v4, 1
	global_load_lds_dwordx4 v2, s[4:5]
	s_mov_b32 m0, s19
	s_add_u32 s6, s6, s22
	global_load_lds_dwordx4 v136, s[4:5]
	s_mov_b32 m0, s20
	s_addc_u32 s7, s7, s16
	s_add_i32 s22, s43, s37
	global_load_lds_dwordx4 v2, s[10:11]
	s_mov_b32 m0, s21
	s_add_i32 s23, s22, 0x2000
	v_mul_lo_u32 v145, v6, s8
	global_load_lds_dwordx4 v136, s[10:11]
	s_mov_b32 m0, s22
	s_add_u32 s26, s6, s2
	v_add_lshl_u32 v134, v4, v145, 1
	global_load_lds_dwordx4 v132, s[6:7]
	s_mov_b32 m0, s23
	s_addc_u32 s27, s7, s3
	s_add_i32 s24, s22, 0x4000
	global_load_lds_dwordx4 v134, s[6:7]
	s_mov_b32 m0, s24
	s_add_i32 s25, s22, 0x6000
	global_load_lds_dwordx4 v132, s[26:27]
	s_mov_b32 m0, s25
	s_cmp_lg_u32 s12, 1
	global_load_lds_dwordx4 v134, s[26:27]
	s_cbranch_scc1 .LBB0_2327
	s_barrier

.LBB0_2332:
	v_mov_b32_e32 v136, v3
	v_cvt_pk_fp8_f32 v136, v124, v125
	v_mov_b32_e32 v124, v3
	v_cvt_pk_fp8_f32 v124, v120, v121
	v_mov_b32_e32 v121, v3
	v_cvt_pk_fp8_f32 v121, v108, v109
	v_mov_b32_e32 v109, v3
	v_cvt_pk_fp8_f32 v109, v100, v101
	v_mov_b32_e32 v137, v3
	v_mov_b32_e32 v125, v3
	v_mov_b32_e32 v120, v3
	v_cvt_pk_fp8_f32 v109, v102, v103 op_sel:[0,0,1]
	v_mov_b32_e32 v103, v3
	v_cvt_pk_fp8_f32 v103, v92, v93
	v_mov_b32_e32 v93, v3
	v_cvt_pk_fp8_f32 v93, v84, v85
	v_mov_b32_e32 v132, v0
	v_cvt_pk_fp8_f32 v137, v128, v129
	v_cvt_pk_fp8_f32 v125, v116, v117
	v_cvt_pk_fp8_f32 v93, v86, v87 op_sel:[0,0,1]
	v_mov_b32_e32 v87, v3
	v_cvt_pk_fp8_f32 v87, v76, v77
	v_cvt_pk_fp8_f32 v120, v112, v113
	v_mov_b32_e32 v108, v3
	v_cvt_pk_fp8_f32 v87, v78, v79 op_sel:[0,0,1]
	v_mov_b32_e32 v79, v3
	v_cvt_pk_fp8_f32 v79, v68, v69
	v_cvt_pk_fp8_f32 v108, v104, v105
	v_lshrrev_b32_e32 v2, 1, v132
	v_readlane_b32 s2, v253, 29
	v_and_or_b32 v132, v132, 15, s15
	v_readlane_b32 s4, v253, 28
	v_and_or_b32 v2, v2, 24, s2
	v_readlane_b32 s100, v253, 30
	s_mov_b32 s101, 0x3fc00000
	s_sub_i32 s100, s100, 16
	s_cmp_lt_i32 s100, 4
	s_cselect_b32 s2, s101, 0x41e00000
	v_add_u32_e32 v132, s4, v132
	v_mov_b32_e32 v102, v3
	v_cvt_pk_fp8_f32 v79, v70, v71 op_sel:[0,0,1]
	v_mov_b32_e32 v70, v3
	v_mov_b32_e32 v71, v3
	s_add_u32 s2, s38, s2
	v_cvt_pk_fp8_f32 v136, v126, v127 op_sel:[0,0,1]
	v_cvt_pk_fp8_f32 v137, v130, v131 op_sel:[0,0,1]
	v_cvt_pk_fp8_f32 v125, v118, v119 op_sel:[0,0,1]
	v_or_b32_e32 v118, 16, v132
	v_cvt_pk_fp8_f32 v120, v114, v115 op_sel:[0,0,1]
	v_cvt_pk_fp8_f32 v121, v110, v111 op_sel:[0,0,1]
	v_cvt_pk_fp8_f32 v102, v96, v97
	v_mov_b32_e32 v92, v3
	v_cvt_pk_fp8_f32 v70, v64, v65
	v_cvt_pk_fp8_f32 v71, v60, v61
	v_or_b32_e32 v2, s16, v2
	s_addc_u32 s3, s39, 0
	v_ashrrev_i32_e32 v133, 31, v132
	v_cvt_pk_fp8_f32 v124, v122, v123 op_sel:[0,0,1]
	v_ashrrev_i32_e32 v119, 31, v118
	v_cvt_pk_fp8_f32 v108, v106, v107 op_sel:[0,0,1]
	v_cvt_pk_fp8_f32 v92, v88, v89
	v_lshl_add_u64 v[134:135], s[2:3], 0, v[2:3]
	v_lshlrev_b64 v[116:117], 10, v[132:133]
	v_lshlrev_b64 v[100:101], 10, v[118:119]
	v_lshl_add_u64 v[116:117], v[134:135], 0, v[116:117]
	v_lshl_add_u64 v[100:101], v[134:135], 0, v[100:101]
	global_store_dwordx2 v[116:117], v[136:137], off
	global_store_dwordx2 v[116:117], v[124:125], off offset:128
	global_store_dwordx2 v[100:101], v[120:121], off
	global_store_dwordx2 v[100:101], v[108:109], off offset:128
	v_or_b32_e32 v100, 32, v132
	v_cvt_pk_fp8_f32 v102, v98, v99 op_sel:[0,0,1]
	v_cvt_pk_fp8_f32 v103, v94, v95 op_sel:[0,0,1]
	v_cvt_pk_fp8_f32 v70, v66, v67 op_sel:[0,0,1]
	v_cvt_pk_fp8_f32 v71, v62, v63 op_sel:[0,0,1]
	v_ashrrev_i32_e32 v101, 31, v100
	v_cvt_pk_fp8_f32 v92, v90, v91 op_sel:[0,0,1]
	v_mov_b32_e32 v63, v3
	s_mov_b32 s2, 0x20000
	v_lshlrev_b64 v[84:85], 10, v[100:101]
	v_cvt_pk_fp8_f32 v63, v52, v53
	v_add_co_u32_e32 v52, vcc, s2, v116
	v_lshl_add_u64 v[84:85], v[134:135], 0, v[84:85]
	s_nop 0
	v_addc_co_u32_e32 v53, vcc, 0, v117, vcc
	global_store_dwordx2 v[84:85], v[102:103], off
	global_store_dwordx2 v[84:85], v[92:93], off offset:128
	global_store_dwordx2 v[52:53], v[70:71], off
	v_mov_b32_e32 v52, v3
	v_mov_b32_e32 v53, v3
	v_cvt_pk_fp8_f32 v52, v48, v49
	v_cvt_pk_fp8_f32 v53, v44, v45
	s_mov_b64 s[2:3], 0x24000
	v_lshl_add_u64 v[44:45], v[116:117], 0, s[2:3]
	v_cvt_pk_fp8_f32 v52, v50, v51 op_sel:[0,0,1]
	v_cvt_pk_fp8_f32 v53, v46, v47 op_sel:[0,0,1]
	v_mov_b32_e32 v47, v3
	s_mov_b32 s2, 0x24000
	v_cvt_pk_fp8_f32 v47, v36, v37
	v_add_co_u32_e32 v36, vcc, s2, v116
	s_mov_b64 s[2:3], 0x28000
	s_nop 0
	v_addc_co_u32_e32 v37, vcc, 0, v117, vcc
	global_store_dwordx2 v[36:37], v[52:53], off
	v_mov_b32_e32 v36, v3
	v_mov_b32_e32 v37, v3
	v_cvt_pk_fp8_f32 v36, v32, v33
	v_cvt_pk_fp8_f32 v37, v28, v29
	v_lshl_add_u64 v[28:29], v[116:117], 0, s[2:3]
	s_mov_b32 s2, 0x28000
	v_cvt_pk_fp8_f32 v36, v34, v35 op_sel:[0,0,1]
	v_cvt_pk_fp8_f32 v37, v30, v31 op_sel:[0,0,1]
	v_mov_b32_e32 v31, v3
	v_cvt_pk_fp8_f32 v31, v20, v21
	v_add_co_u32_e32 v20, vcc, s2, v116
	v_mov_b32_e32 v86, v3
	s_nop 0
	v_addc_co_u32_e32 v21, vcc, 0, v117, vcc
	global_store_dwordx2 v[20:21], v[36:37], off
	v_mov_b32_e32 v21, v3
	v_cvt_pk_fp8_f32 v21, v12, v13
	v_mov_b32_e32 v78, v3
	v_mov_b32_e32 v62, v3
	v_mov_b32_e32 v46, v3
	v_mov_b32_e32 v30, v3
	v_mov_b32_e32 v20, v3
	v_cvt_pk_fp8_f32 v86, v80, v81
	v_cvt_pk_fp8_f32 v78, v72, v73
	v_cvt_pk_fp8_f32 v62, v56, v57
	v_cvt_pk_fp8_f32 v46, v40, v41
	v_cvt_pk_fp8_f32 v30, v24, v25
	v_cvt_pk_fp8_f32 v20, v16, v17
	v_cvt_pk_fp8_f32 v21, v14, v15 op_sel:[0,0,1]
	v_mov_b32_e32 v14, v3
	v_mov_b32_e32 v15, v3
	v_cvt_pk_fp8_f32 v14, v8, v9
	v_cvt_pk_fp8_f32 v15, v4, v5
	v_or_b32_e32 v84, 48, v132
	v_cvt_pk_fp8_f32 v86, v82, v83 op_sel:[0,0,1]
	v_cvt_pk_fp8_f32 v78, v74, v75 op_sel:[0,0,1]
	v_cvt_pk_fp8_f32 v62, v58, v59 op_sel:[0,0,1]
	v_cvt_pk_fp8_f32 v63, v54, v55 op_sel:[0,0,1]
	v_cvt_pk_fp8_f32 v46, v42, v43 op_sel:[0,0,1]
	v_cvt_pk_fp8_f32 v47, v38, v39 op_sel:[0,0,1]
	v_cvt_pk_fp8_f32 v30, v26, v27 op_sel:[0,0,1]
	v_cvt_pk_fp8_f32 v31, v22, v23 op_sel:[0,0,1]
	v_cvt_pk_fp8_f32 v20, v18, v19 op_sel:[0,0,1]
	v_ashrrev_i32_e32 v85, 31, v84
	v_cvt_pk_fp8_f32 v14, v10, v11 op_sel:[0,0,1]
	v_cvt_pk_fp8_f32 v15, v6, v7 op_sel:[0,0,1]
	v_lshlrev_b64 v[76:77], 10, v[84:85]
	v_add_co_u32_e32 v4, vcc, 0x2c000, v116
	v_lshl_add_u64 v[68:69], v[134:135], 0, v[76:77]
	v_lshl_add_u64 v[60:61], v[116:117], 0, s[28:29]
	s_mov_b64 s[2:3], 0x2c000
	v_addc_co_u32_e32 v5, vcc, 0, v117, vcc
	global_store_dwordx2 v[68:69], v[86:87], off
	global_store_dwordx2 v[68:69], v[78:79], off offset:128
	global_store_dwordx2 v[60:61], v[62:63], off offset:128
	global_store_dwordx2 v[44:45], v[46:47], off offset:128
	global_store_dwordx2 v[28:29], v[30:31], off offset:128
	v_lshl_add_u64 v[12:13], v[116:117], 0, s[2:3]
	global_store_dwordx2 v[4:5], v[20:21], off
	global_store_dwordx2 v[12:13], v[14:15], off offset:128
	s_waitcnt vmcnt(0)
	s_barrier
